# v20 + late-phase weight transposes (items >= 4112) moved from P0 into the idle slot of P1 (workgroups 128..255)
# baseline (speedup 1.0000x reference)
; __global__ void __launch_bounds__(512, 2) fwd_megakernel(Params P) {
;     ...
;         constexpr int I0 = 16 * 72, I1 = 16 * 32, I2 = 6 * 24, I3 = 4 * 32, I4 = 16 * 32, I5 = 16 * 16, I6 = 8 * 32, I7 = 16 * 176, I8 = 44 * 32;
;         constexpr int NITEMS = I0 + I1 + I2 + I3 + I4 + I5 + I6 + I7 + I8;
;         for (int it = gw; it < NITEMS; it += NGW) {
;             int r = it;
;             if (r < I0) { const int g = r % 72, kb = r / 72; int sc;
;                 if (g < 64) sc = 32 * g; else if (g == 64) sc = 2048; else if (g == 65) sc = 2080; else if (g == 66) sc = 2176; else if (g == 67) sc = -1;
;                 else if (g == 68) sc = 2112; else if (g == 69) sc = 2144; else if (g == 70) sc = 2208; else sc = -1;
;                 transpose_item(P.w_in, 2240, sc, nullptr, Wt_in, 1024, 32 * g, 64 * kb, scr, lane); continue; } r -= I0;
.LBB0_19:
	s_or_b64 exec, exec, s[2:3]
	v_mov_b32_e32 v9, v242
	s_lshl_b32 s96, s33, 3
	v_readfirstlane_b32 s0, v9
	s_ashr_i32 s29, s0, 6
	s_lshl_b32 s28, s34, 3
	s_add_i32 s4, s29, s96
	s_mov_b64 s[8:9], 0
	s_add_u32 s68, s26, s8
	v_and_b32_e32 v11, 63, v9
	s_addc_u32 s69, s27, s9
	s_cmpk_lt_i32 s4, 4112
	v_and_b32_e32 v8, 31, v9
	v_lshlrev_b32_e32 v10, 3, v11
	s_cbranch_scc0 .LBB0_402
	v_readlane_b32 s80, v254, 0
	s_cmp_lg_u64 s[14:15], 0
	v_readlane_b32 s88, v254, 8
	v_readlane_b32 s89, v254, 9
	s_cselect_b64 s[6:7], -1, 0
	s_cmp_lg_u64 s[88:89], 0
	s_cselect_b64 s[70:71], -1, 0
	s_cmp_lg_u64 s[50:51], 0
	s_cselect_b64 s[72:73], -1, 0
	s_cmp_lg_u64 s[46:47], 0
	s_cselect_b64 s[74:75], -1, 0
	s_lshl_b32 s0, s29, 14
	v_lshrrev_b32_e32 v46, 5, v11
	s_add_i32 s2, s0, 0
	v_lshlrev_b32_e32 v0, 2, v8
	v_mul_u32_u24_e32 v4, 0x84, v46
	v_mov_b32_e32 v1, 0
	v_add3_u32 v47, s2, v0, v4
	v_and_b32_e32 v4, 56, v10
	v_mul_u32_u24_e32 v12, 0x84, v4
	v_lshlrev_b32_e32 v4, 1, v4
	v_mov_b32_e32 v5, v1
	v_lshrrev_b32_e32 v48, 3, v11
	v_lshl_add_u64 v[4:5], s[68:69], 0, v[4:5]
	s_mov_b64 s[0:1], 0x1690000
	v_lshl_add_u64 v[6:7], v[4:5], 0, s[0:1]
	v_lshlrev_b32_e32 v13, 2, v48
	s_mov_b64 s[0:1], 0xb90000
	v_add3_u32 v49, s2, v12, v13
	v_lshl_add_u64 v[12:13], v[4:5], 0, s[0:1]
	s_mov_b64 s[0:1], 0xa90000
	v_lshl_add_u64 v[16:17], v[4:5], 0, s[0:1]
	s_mov_b64 s[0:1], 0x990000
	v_lshl_add_u64 v[20:21], v[4:5], 0, s[0:1]
	s_mov_b64 s[0:1], 0x790000
	v_lshl_add_u64 v[24:25], v[4:5], 0, s[0:1]
	s_mov_b64 s[0:1], 0x710000
	v_lshl_add_u64 v[28:29], v[4:5], 0, s[0:1]
	s_mov_b64 s[0:1], 0x680000
	v_readlane_b32 s81, v254, 1
	v_readlane_b32 s86, v254, 6
	v_readlane_b32 s87, v254, 7
	v_readlane_b32 s92, v254, 12
	v_readlane_b32 s93, v254, 13
	v_readlane_b32 s94, v254, 14
	v_readlane_b32 s95, v254, 15
	v_lshl_add_u64 v[32:33], v[4:5], 0, s[0:1]
	s_mov_b64 s[0:1], 0x480000
	s_mov_b32 s77, 0
	v_lshl_add_u64 v[2:3], s[20:21], 0, v[0:1]
	v_or_b32_e32 v50, 8, v48
	v_or_b32_e32 v51, 16, v48
	v_or_b32_e32 v52, 24, v48
	v_lshl_add_u64 v[14:15], s[12:13], 0, v[0:1]
	v_lshl_add_u64 v[18:19], s[92:93], 0, v[0:1]
	v_lshl_add_u64 v[22:23], s[86:87], 0, v[0:1]
	v_lshl_add_u64 v[26:27], s[80:81], 0, v[0:1]
	v_lshl_add_u64 v[30:31], s[48:49], 0, v[0:1]
	v_lshl_add_u64 v[34:35], s[94:95], 0, v[0:1]
	v_lshl_add_u64 v[36:37], v[4:5], 0, s[0:1]
	v_lshl_add_u64 v[38:39], s[44:45], 0, v[0:1]
	s_lshl_b32 s5, s4, 5
	s_lshl_b32 s44, s28, 5
	s_lshl_b32 s45, s4, 1
	s_lshl_b32 s48, s28, 1
	s_lshl_b32 s49, s4, 2
	s_lshl_b32 s52, s28, 2
	v_lshlrev_b32_e32 v40, 2, v8
	s_movk_i32 s53, 0x2c00
	s_movk_i32 s58, 0xc00
	s_movk_i32 s59, 0x2300
	v_add_u32_e32 v53, 0x400, v47
	v_add_u32_e32 v54, 0x800, v47
	v_add_u32_e32 v55, 0xc00, v47
	v_add_u32_e32 v56, 0x1000, v47
	v_add_u32_e32 v57, 0x1400, v47
	v_add_u32_e32 v58, 0x1800, v47
	v_add_u32_e32 v59, 0x1c00, v47
	s_mov_b32 s64, s4
	v_readlane_b32 s82, v254, 2
	v_readlane_b32 s83, v254, 3
	v_readlane_b32 s84, v254, 4
	v_readlane_b32 s85, v254, 5
	v_readlane_b32 s90, v254, 10
	v_readlane_b32 s91, v254, 11
	s_branch .LBB0_23

; __global__ void __launch_bounds__(512, 2) fwd_megakernel(Params P) {
;     ...
;         for (int it = gw; it < NITEMS; it += NGW) {
.LBB0_22:
	s_add_i32 s64, s64, s28
	s_add_i32 s5, s5, s44
	s_add_i32 s45, s45, s48
	s_add_i32 s49, s49, s52
	s_cmpk_gt_i32 s64, 4111
	s_cbranch_scc1 .LBB0_402

; #define REP(k) for (int rep_ = 0; rep_ < (((PHREP >> (k)) & 1) ? 2 : 1); ++rep_)
; __global__ void __launch_bounds__(512, 2) fwd_megakernel(Params P) {
;     ...
;         constexpr int I0 = 16 * 72, I1 = 16 * 32, I2 = 6 * 24, I3 = 4 * 32, I4 = 16 * 32, I5 = 16 * 16, I6 = 8 * 32, I7 = 16 * 176, I8 = 44 * 32;
;         constexpr int NITEMS = I0 + I1 + I2 + I3 + I4 + I5 + I6 + I7 + I8;
;         for (int it = gw; it < NITEMS; it += NGW) {
;             int r = it;
;             if (r < I0) { const int g = r % 72, kb = r / 72; int sc;
;                 if (g < 64) sc = 32 * g; else if (g == 64) sc = 2048; else if (g == 65) sc = 2080; else if (g == 66) sc = 2176; else if (g == 67) sc = -1;
;                 else if (g == 68) sc = 2112; else if (g == 69) sc = 2144; else if (g == 70) sc = 2208; else sc = -1;
;                 transpose_item(P.w_in, 2240, sc, nullptr, Wt_in, 1024, 32 * g, 64 * kb, scr, lane); continue; } r -= I0;
;     ...
;     if (PH(1)) REP(1) {
;         PHASE_VARS
;         { pg8::Gemm g{HB, Wt_in, T, DIN_PAD, 1024}; pg8::StaticOrder S; S.init(T, DIN_PAD, G, bid);
;           epi::Proj E{QKV, CQ, CKV, KPE, (float*)(ws + WS_RS2 + 262144), TC, TS}; pg8::gemm_phase<epi::Proj, pg8::StaticOrder, true, true>(ring, g, S, E); }
;         { pg8::Gemm g{MK, Wt_mkv, TM, 1024, 1024}; pg8::StaticOrder S; S.init(TM, 1024, G, (bid + G - 128) % G);
;           epi::Plain E{MKV, 1024}; pg8::gemm_phase<epi::Plain, pg8::StaticOrder, true, true>(ring, g, S, E); }
;     }
.LBB0_758:
	s_waitcnt vmcnt(0)
	s_cmpk_lt_u32 s33, 0x80
	s_cbranch_scc1 .Ltq_skip
	v_writelane_b32 v252, s0, 0
	v_writelane_b32 v252, s1, 1
	v_writelane_b32 v252, s2, 2
	v_writelane_b32 v252, s3, 3
	v_writelane_b32 v252, s4, 4
	v_writelane_b32 v252, s5, 5
	v_writelane_b32 v252, s6, 6
	v_writelane_b32 v252, s7, 7
	v_writelane_b32 v252, s8, 8
	v_writelane_b32 v252, s9, 9
	v_writelane_b32 v252, s10, 10
	v_writelane_b32 v252, s11, 11
	v_writelane_b32 v252, s12, 12
	v_writelane_b32 v252, s13, 13
	v_writelane_b32 v252, s14, 14
	v_writelane_b32 v252, s15, 15
	v_writelane_b32 v252, s16, 16
	v_writelane_b32 v252, s17, 17
	v_writelane_b32 v252, s18, 18
	v_writelane_b32 v252, s19, 19
	v_writelane_b32 v252, s20, 20
	v_writelane_b32 v252, s21, 21
	v_writelane_b32 v252, s28, 22
	v_writelane_b32 v252, s29, 23
	v_writelane_b32 v252, s36, 24
	v_writelane_b32 v252, s37, 25
	v_writelane_b32 v252, s38, 26
	v_writelane_b32 v252, s39, 27
	v_writelane_b32 v252, s40, 28
	v_writelane_b32 v252, s41, 29
	v_writelane_b32 v252, s42, 30
	v_writelane_b32 v252, s43, 31
	v_writelane_b32 v252, s44, 32
	v_writelane_b32 v252, s45, 33
	v_writelane_b32 v252, s46, 34
	v_writelane_b32 v252, s47, 35
	v_writelane_b32 v252, s48, 36
	v_writelane_b32 v252, s49, 37
	v_writelane_b32 v252, s50, 38
	v_writelane_b32 v252, s51, 39
	v_writelane_b32 v252, s52, 40
	v_writelane_b32 v252, s53, 41
	v_writelane_b32 v252, s58, 42
	v_writelane_b32 v252, s59, 43
	v_writelane_b32 v252, s64, 44
	v_writelane_b32 v252, s68, 45
	v_writelane_b32 v252, s69, 46
	v_writelane_b32 v252, s70, 47
	v_writelane_b32 v252, s71, 48
	v_writelane_b32 v252, s72, 49
	v_writelane_b32 v252, s73, 50
	v_writelane_b32 v252, s74, 51
	v_writelane_b32 v252, s75, 52
	v_writelane_b32 v252, s76, 53
	v_writelane_b32 v252, s77, 54
	v_writelane_b32 v252, s80, 55
	v_writelane_b32 v252, s81, 56
	v_writelane_b32 v252, s82, 57
	v_writelane_b32 v252, s83, 58
	v_writelane_b32 v252, s84, 59
	v_writelane_b32 v252, s85, 60
	v_writelane_b32 v252, s86, 61
	v_writelane_b32 v252, s87, 62
	v_writelane_b32 v252, s88, 63
	v_writelane_b32 v253, s89, 0
	v_writelane_b32 v253, s90, 1
	v_writelane_b32 v253, s91, 2
	v_writelane_b32 v253, s92, 3
	v_writelane_b32 v253, s93, 4
	v_writelane_b32 v253, s94, 5
	v_writelane_b32 v253, s95, 6
	v_writelane_b32 v253, s96, 7
	s_load_dwordx16 s[36:51], s[98:99], 0x0
	s_load_dwordx8 s[12:19], s[98:99], 0x80
	s_load_dwordx2 s[20:21], s[98:99], 0xa0
	s_waitcnt lgkmcnt(0)
	v_mov_b32_e32 v9, v242
	s_lshl_b32 s96, s33, 3
	v_readfirstlane_b32 s0, v9
	s_ashr_i32 s29, s0, 6
	s_movk_i32 s28, 0x400
	s_add_i32 s4, s29, s96
	s_addk_i32 s4, 3088
	s_mov_b64 s[8:9], 0
	s_add_u32 s68, s26, s8
	v_and_b32_e32 v11, 63, v9
	s_addc_u32 s69, s27, s9
	s_cmpk_lt_i32 s4, 0x1c10
	v_and_b32_e32 v8, 31, v9
	v_lshlrev_b32_e32 v10, 3, v11
	s_cbranch_scc0 .Ltq_done
	v_readlane_b32 s80, v254, 0
	s_cmp_lg_u64 s[14:15], 0
	v_readlane_b32 s88, v254, 8
	v_readlane_b32 s89, v254, 9
	s_cselect_b64 s[6:7], -1, 0
	s_cmp_lg_u64 s[88:89], 0
	s_cselect_b64 s[70:71], -1, 0
	s_cmp_lg_u64 s[50:51], 0
	s_cselect_b64 s[72:73], -1, 0
	s_cmp_lg_u64 s[46:47], 0
	s_cselect_b64 s[74:75], -1, 0
	s_lshl_b32 s0, s29, 14
	v_lshrrev_b32_e32 v46, 5, v11
	s_add_i32 s2, s0, 0
	v_lshlrev_b32_e32 v0, 2, v8
	v_mul_u32_u24_e32 v4, 0x84, v46
	v_mov_b32_e32 v1, 0
	v_add3_u32 v47, s2, v0, v4
	v_and_b32_e32 v4, 56, v10
	v_mul_u32_u24_e32 v12, 0x84, v4
	v_lshlrev_b32_e32 v4, 1, v4
	v_mov_b32_e32 v5, v1
	v_lshrrev_b32_e32 v48, 3, v11
	v_lshl_add_u64 v[4:5], s[68:69], 0, v[4:5]
	s_mov_b64 s[0:1], 0x1690000
	v_lshl_add_u64 v[6:7], v[4:5], 0, s[0:1]
	v_lshlrev_b32_e32 v13, 2, v48
	s_mov_b64 s[0:1], 0xb90000
	v_add3_u32 v49, s2, v12, v13
	v_lshl_add_u64 v[12:13], v[4:5], 0, s[0:1]
	s_mov_b64 s[0:1], 0xa90000
	v_lshl_add_u64 v[16:17], v[4:5], 0, s[0:1]
	s_mov_b64 s[0:1], 0x990000
	v_lshl_add_u64 v[20:21], v[4:5], 0, s[0:1]
	s_mov_b64 s[0:1], 0x790000
	v_lshl_add_u64 v[24:25], v[4:5], 0, s[0:1]
	s_mov_b64 s[0:1], 0x710000
	v_lshl_add_u64 v[28:29], v[4:5], 0, s[0:1]
	s_mov_b64 s[0:1], 0x680000
	v_readlane_b32 s81, v254, 1
	v_readlane_b32 s86, v254, 6
	v_readlane_b32 s87, v254, 7
	v_readlane_b32 s92, v254, 12
	v_readlane_b32 s93, v254, 13
	v_readlane_b32 s94, v254, 14
	v_readlane_b32 s95, v254, 15
	v_lshl_add_u64 v[32:33], v[4:5], 0, s[0:1]
	s_mov_b64 s[0:1], 0x480000
	s_mov_b32 s77, 0
	v_lshl_add_u64 v[2:3], s[20:21], 0, v[0:1]
	v_or_b32_e32 v50, 8, v48
	v_or_b32_e32 v51, 16, v48
	v_or_b32_e32 v52, 24, v48
	v_lshl_add_u64 v[14:15], s[12:13], 0, v[0:1]
	v_lshl_add_u64 v[18:19], s[92:93], 0, v[0:1]
	v_lshl_add_u64 v[22:23], s[86:87], 0, v[0:1]
	v_lshl_add_u64 v[26:27], s[80:81], 0, v[0:1]
	v_lshl_add_u64 v[30:31], s[48:49], 0, v[0:1]
	v_lshl_add_u64 v[34:35], s[94:95], 0, v[0:1]
	v_lshl_add_u64 v[36:37], v[4:5], 0, s[0:1]
	v_lshl_add_u64 v[38:39], s[44:45], 0, v[0:1]
	s_lshl_b32 s5, s4, 5
	s_lshl_b32 s44, s28, 5
	s_lshl_b32 s45, s4, 1
	s_lshl_b32 s48, s28, 1
	s_lshl_b32 s49, s4, 2
	s_lshl_b32 s52, s28, 2
	v_lshlrev_b32_e32 v40, 2, v8
	s_movk_i32 s53, 0x2c00
	s_movk_i32 s58, 0xc00
	s_movk_i32 s59, 0x2300
	v_add_u32_e32 v53, 0x400, v47
	v_add_u32_e32 v54, 0x800, v47
	v_add_u32_e32 v55, 0xc00, v47
	v_add_u32_e32 v56, 0x1000, v47
	v_add_u32_e32 v57, 0x1400, v47
	v_add_u32_e32 v58, 0x1800, v47
	v_add_u32_e32 v59, 0x1c00, v47
	s_mov_b32 s64, s4
	v_readlane_b32 s82, v254, 2
	v_readlane_b32 s83, v254, 3
	v_readlane_b32 s84, v254, 4
	v_readlane_b32 s85, v254, 5
	v_readlane_b32 s90, v254, 10
	v_readlane_b32 s91, v254, 11
	s_branch .Ltq_23

; __device__ __forceinline__ unsigned xb_ld(unsigned* p)              { return __hip_atomic_load(p, __ATOMIC_RELAXED, __HIP_MEMORY_SCOPE_AGENT); }
; __device__ __forceinline__ void xcd_barrier_complete(unsigned* bar, unsigned x, unsigned& nloc, unsigned& nx) {
;     const unsigned G = gridDim.x * gridDim.y * gridDim.z;
;     unsigned sum, cnt, mine, sp = 0u;
;     for (;;) {
;         sum = 0u; cnt = 0u; mine = 0u;
; #pragma unroll
;         for (unsigned j = 0; j < 16; ++j) { const unsigned c = xb_ld(&bar[XB_XCNT(j)]); sum += c; cnt += (c > 0u) ? 1u : 0u; mine = (j == x) ? c : mine; }
; __device__ __forceinline__ void xcd_barrier(const XcdBarrier& b) {
;     asm volatile("s_waitcnt vmcnt(0)" ::: "memory");
;     __syncthreads();
;     if (threadIdx.x == 0) {
;         unsigned* bar = b.bar;
;         __builtin_amdgcn_s_waitcnt(0);
;         unsigned nloc = b.st[0], nx = b.st[1];
;         if (nloc == 0u) { xcd_barrier_complete(bar, b.x, nloc, nx); b.st[0] = nloc; b.st[1] = nx; }
.Ltq_done:
	s_waitcnt vmcnt(0) lgkmcnt(0)
	s_nop 3
	v_readlane_b32 s0, v252, 0
	v_readlane_b32 s1, v252, 1
	v_readlane_b32 s2, v252, 2
	v_readlane_b32 s3, v252, 3
	v_readlane_b32 s4, v252, 4
	v_readlane_b32 s5, v252, 5
	v_readlane_b32 s6, v252, 6
	v_readlane_b32 s7, v252, 7
	v_readlane_b32 s8, v252, 8
	v_readlane_b32 s9, v252, 9
	v_readlane_b32 s10, v252, 10
	v_readlane_b32 s11, v252, 11
	v_readlane_b32 s12, v252, 12
	v_readlane_b32 s13, v252, 13
	v_readlane_b32 s14, v252, 14
	v_readlane_b32 s15, v252, 15
	v_readlane_b32 s16, v252, 16
	v_readlane_b32 s17, v252, 17
	v_readlane_b32 s18, v252, 18
	v_readlane_b32 s19, v252, 19
	v_readlane_b32 s20, v252, 20
	v_readlane_b32 s21, v252, 21
	v_readlane_b32 s28, v252, 22
	v_readlane_b32 s29, v252, 23
	v_readlane_b32 s36, v252, 24
	v_readlane_b32 s37, v252, 25
	v_readlane_b32 s38, v252, 26
	v_readlane_b32 s39, v252, 27
	v_readlane_b32 s40, v252, 28
	v_readlane_b32 s41, v252, 29
	v_readlane_b32 s42, v252, 30
	v_readlane_b32 s43, v252, 31
	v_readlane_b32 s44, v252, 32
	v_readlane_b32 s45, v252, 33
	v_readlane_b32 s46, v252, 34
	v_readlane_b32 s47, v252, 35
	v_readlane_b32 s48, v252, 36
	v_readlane_b32 s49, v252, 37
	v_readlane_b32 s50, v252, 38
	v_readlane_b32 s51, v252, 39
	v_readlane_b32 s52, v252, 40
	v_readlane_b32 s53, v252, 41
	v_readlane_b32 s58, v252, 42
	v_readlane_b32 s59, v252, 43
	v_readlane_b32 s64, v252, 44
	v_readlane_b32 s68, v252, 45
	v_readlane_b32 s69, v252, 46
	v_readlane_b32 s70, v252, 47
	v_readlane_b32 s71, v252, 48
	v_readlane_b32 s72, v252, 49
	v_readlane_b32 s73, v252, 50
	v_readlane_b32 s74, v252, 51
	v_readlane_b32 s75, v252, 52
	v_readlane_b32 s76, v252, 53
	v_readlane_b32 s77, v252, 54
	v_readlane_b32 s80, v252, 55
	v_readlane_b32 s81, v252, 56
	v_readlane_b32 s82, v252, 57
	v_readlane_b32 s83, v252, 58
	v_readlane_b32 s84, v252, 59
	v_readlane_b32 s85, v252, 60
	v_readlane_b32 s86, v252, 61
	v_readlane_b32 s87, v252, 62
	v_readlane_b32 s88, v252, 63
	v_readlane_b32 s89, v253, 0
	v_readlane_b32 s90, v253, 1
	v_readlane_b32 s91, v253, 2
	v_readlane_b32 s92, v253, 3
	v_readlane_b32 s93, v253, 4
	v_readlane_b32 s94, v253, 5
	v_readlane_b32 s95, v253, 6
	v_readlane_b32 s96, v253, 7
	s_nop 3
.Ltq_skip:
	v_readlane_b32 s2, v254, 18
	v_readlane_b32 s3, v254, 19
	s_waitcnt vmcnt(0) lgkmcnt(0)
	s_barrier
	s_and_saveexec_b64 s[0:1], s[2:3]
	s_xor_b64 s[2:3], exec, s[0:1]
	s_cbranch_execz .LBB0_811
	s_add_i32 s0, 0, 0x20800
	v_mov_b32_e32 v0, s0
	s_waitcnt vmcnt(0) expcnt(0) lgkmcnt(0)
	ds_read_b32 v2, v0
	s_add_i32 s0, 0, 0x20804
	v_mov_b32_e32 v0, s0
	ds_read_b32 v0, v0
	s_waitcnt lgkmcnt(1)
	v_cmp_ne_u32_e32 vcc, 0, v2
	s_cbranch_vccnz .LBB0_774
	s_add_u32 s4, s26, 0x1f00200
	s_addc_u32 s5, s27, 0
	s_add_u32 s6, s26, 0x1f00400
	s_addc_u32 s7, s27, 0
	s_add_u32 s8, s26, 0x1f00500
	s_addc_u32 s9, s27, 0
	s_add_u32 s14, s26, 0x1f00600
	s_addc_u32 s15, s27, 0
	s_add_u32 s16, s26, 0x1f00700
	s_addc_u32 s17, s27, 0
	s_add_u32 s18, s26, 0x1f00800
	s_addc_u32 s19, s27, 0
	s_add_u32 s20, s26, 0x1f00900
	s_addc_u32 s21, s27, 0
	s_add_u32 s38, s26, 0x1f00a00
	s_addc_u32 s39, s27, 0
	s_add_u32 s42, s26, 0x1f00b00
	s_addc_u32 s43, s27, 0
	s_add_u32 s44, s26, 0x1f00c00
	s_addc_u32 s45, s27, 0
	s_add_u32 s46, s26, 0x1f00d00
	s_addc_u32 s47, s27, 0
	s_add_u32 s48, s26, 0x1f00e00
	s_addc_u32 s49, s27, 0
	s_add_u32 s50, s26, 0x1f00f00
	s_addc_u32 s51, s27, 0
	s_add_u32 s52, s26, 0x1f01000
	s_addc_u32 s53, s27, 0
	s_add_u32 s58, s26, 0x1f01100
	s_addc_u32 s59, s27, 0
	s_add_u32 s60, s26, 0x1f01200
	s_addc_u32 s61, s27, 0
	s_mul_i32 s0, s35, s54
	s_add_u32 s62, s26, 0x1f01300
	s_mul_i32 s0, s0, s34
	s_addc_u32 s63, s27, 0
	s_mov_b32 s1, 1
	v_mov_b32_e32 v16, 0
	s_branch .LBB0_762
